# baseline (speedup 1.0000x reference)
; __global__ void __launch_bounds__(NTHREADS, 2) fwd_megakernel(Params p_arg) {
;     ...
;       for (int kvh = 0; kvh < 2; ++kvh) {
; #pragma unroll 2
;         for (int idx = tid; idx < 3072; idx += NTHREADS) {
;           const int key = idx >> 3, ch = (idx & 7) * 8;
;           const int pos = nb * 128 - 128 + key;
;           uint4 kv = make_uint4(0, 0, 0, 0), vv = make_uint4(0, 0, 0, 0);
;           if (pos >= 0 && pos < SEQ) {
;             const size_t tk = (size_t)b * SEQ + pos;
;             kv = *(const uint4*)(ZKp + tk * 128 + kvh * 64 + ch);
;             vv = *(const uint4*)(ZVAp + tk * 128 + kvh * 64 + ch);
;           }
;           *(uint4*)(Ks + key * 72 + ch) = kv;
;           uint32_t wv[4] = {vv.x, vv.y, vv.z, vv.w};
; #pragma unroll
;           for (int i = 0; i < 8; ++i) VT[(ch + i) * 392 + key] = (u16)((i & 1) ? (wv[i >> 1] >> 16) : (wv[i >> 1] & 0xffffu));
;         }
.LBB0_299:
	s_mov_b64 s[14:15], exec
	v_mbcnt_lo_u32_b32 v0, -1, 0
	v_mbcnt_hi_u32_b32 v0, -1, v0
	v_readlane_b32 s0, v255, 0
	s_and_b32 s16, s99, 31
	s_add_i32 s1, s36, s47
	s_nop 0
	v_add_u32_e32 v0, s0, v0
	v_lshrrev_b32_e32 v2, 3, v0
	v_and_b32_e32 v3, 7, v0
	v_add_u32_e32 v4, s1, v2
	v_ashrrev_i32_e32 v5, 31, v4
	v_lshlrev_b64 v[4:5], 8, v[4:5]
	s_lshl_b32 s0, s28, 7
	v_lshlrev_b32_e32 v6, 4, v3
	v_add_u32_e32 v6, s0, v6
	v_mov_b32_e32 v7, 0
	v_lshl_add_u64 v[4:5], v[4:5], 0, v[6:7]
	s_mov_b32 s0, s21
	s_mov_b32 s1, s20
	v_lshl_add_u64 v[8:9], v[4:5], 0, s[0:1]
	s_mov_b32 s0, s44
	s_mov_b32 s1, s33
	v_lshl_add_u64 v[10:11], v[4:5], 0, s[0:1]
	s_mov_b64 s[0:1], 0x4000
	s_cmp_eq_u32 s16, 0
	s_cbranch_scc1 .Lkvz_0
	global_load_dwordx4 v[16:19], v[8:9], off
	global_load_dwordx4 v[20:23], v[10:11], off
	s_branch .Lkvn_0
.Lkvz_0:
	v_mov_b32_e32 v16, 0
	v_mov_b32_e32 v17, 0
	v_mov_b32_e32 v18, 0
	v_mov_b32_e32 v19, 0
	v_mov_b32_e32 v20, 0
	v_mov_b32_e32 v21, 0
	v_mov_b32_e32 v22, 0
	v_mov_b32_e32 v23, 0
.Lkvn_0:
	v_lshl_add_u64 v[8:9], v[8:9], 0, s[0:1]
	v_lshl_add_u64 v[10:11], v[10:11], 0, s[0:1]
	s_cmp_eq_u32 s16, 0
	s_cbranch_scc1 .Lkvz_1
	global_load_dwordx4 v[24:27], v[8:9], off
	global_load_dwordx4 v[28:31], v[10:11], off
	s_branch .Lkvn_1
.Lkvz_1:
	v_mov_b32_e32 v24, 0
	v_mov_b32_e32 v25, 0
	v_mov_b32_e32 v26, 0
	v_mov_b32_e32 v27, 0
	v_mov_b32_e32 v28, 0
	v_mov_b32_e32 v29, 0
	v_mov_b32_e32 v30, 0
	v_mov_b32_e32 v31, 0
.Lkvn_1:
	v_lshl_add_u64 v[8:9], v[8:9], 0, s[0:1]
	v_lshl_add_u64 v[10:11], v[10:11], 0, s[0:1]
	global_load_dwordx4 v[32:35], v[8:9], off
	global_load_dwordx4 v[36:39], v[10:11], off
	v_lshl_add_u64 v[8:9], v[8:9], 0, s[0:1]
	v_lshl_add_u64 v[10:11], v[10:11], 0, s[0:1]
	global_load_dwordx4 v[40:43], v[8:9], off
	global_load_dwordx4 v[44:47], v[10:11], off
	v_lshl_add_u64 v[8:9], v[8:9], 0, s[0:1]
	v_lshl_add_u64 v[10:11], v[10:11], 0, s[0:1]
	s_cmp_eq_u32 s16, 31
	s_cbranch_scc1 .Lkvz_4
	global_load_dwordx4 v[48:51], v[8:9], off
	global_load_dwordx4 v[52:55], v[10:11], off
	s_branch .Lkvn_4
.Lkvz_4:
	v_mov_b32_e32 v48, 0
	v_mov_b32_e32 v49, 0
	v_mov_b32_e32 v50, 0
	v_mov_b32_e32 v51, 0
	v_mov_b32_e32 v52, 0
	v_mov_b32_e32 v53, 0
	v_mov_b32_e32 v54, 0
	v_mov_b32_e32 v55, 0
.Lkvn_4:
	v_lshl_add_u64 v[8:9], v[8:9], 0, s[0:1]
	v_lshl_add_u64 v[10:11], v[10:11], 0, s[0:1]
	s_cmp_eq_u32 s16, 31
	s_cbranch_scc1 .Lkvz_5
	global_load_dwordx4 v[56:59], v[8:9], off
	global_load_dwordx4 v[60:63], v[10:11], off
	s_branch .Lkvn_5
.Lkvz_5:
	v_mov_b32_e32 v56, 0
	v_mov_b32_e32 v57, 0
	v_mov_b32_e32 v58, 0
	v_mov_b32_e32 v59, 0
	v_mov_b32_e32 v60, 0
	v_mov_b32_e32 v61, 0
	v_mov_b32_e32 v62, 0
	v_mov_b32_e32 v63, 0
.Lkvn_5:
	v_mul_u32_u24_e32 v12, 0x90, v2
	v_lshl_add_u32 v12, v3, 4, v12
	v_mul_u32_u24_e32 v13, 0x1880, v3
	v_lshl_add_u32 v13, v2, 1, v13
	v_and_b32_e32 v64, 1, v3
	v_cmp_ne_u32_e64 s[18:19], 0, v64
	v_and_b32_e32 v64, 2, v3
	v_cmp_ne_u32_e64 s[24:25], 0, v64
	v_and_b32_e32 v64, 4, v3
	v_cmp_ne_u32_e64 s[92:93], 0, v64
	s_movk_i32 s16, 0x310
	v_add_u32_e32 v64, 0, v3
	v_and_b32_e32 v64, 7, v64
	v_mad_u32_u24 v4, v64, s16, v13
	v_add_u32_e32 v64, 1, v3
	v_and_b32_e32 v64, 7, v64
	v_mad_u32_u24 v5, v64, s16, v13
	v_add_u32_e32 v64, 2, v3
	v_and_b32_e32 v64, 7, v64
	v_mad_u32_u24 v6, v64, s16, v13
	v_add_u32_e32 v64, 3, v3
	v_and_b32_e32 v64, 7, v64
	v_mad_u32_u24 v7, v64, s16, v13
	v_add_u32_e32 v64, 4, v3
	v_and_b32_e32 v64, 7, v64
	v_mad_u32_u24 v8, v64, s16, v13
	v_add_u32_e32 v64, 5, v3
	v_and_b32_e32 v64, 7, v64
	v_mad_u32_u24 v9, v64, s16, v13
	v_add_u32_e32 v64, 6, v3
	v_and_b32_e32 v64, 7, v64
	v_mad_u32_u24 v10, v64, s16, v13
	v_add_u32_e32 v64, 7, v3
	v_and_b32_e32 v64, 7, v64
	v_mad_u32_u24 v11, v64, s16, v13
	s_waitcnt vmcnt(0)
; __global__ void __launch_bounds__(NTHREADS, 2) fwd_megakernel(Params p_arg) {
;     ...
;           *(uint4*)(Ks + key * 72 + ch) = kv;
;           uint32_t wv[4] = {vv.x, vv.y, vv.z, vv.w};
; #pragma unroll
;           for (int i = 0; i < 8; ++i) VT[(ch + i) * 392 + key] = (u16)((i & 1) ? (wv[i >> 1] >> 16) : (wv[i >> 1] & 0xffffu));
	ds_write_b128 v12, v[16:19]
	v_alignbit_b32 v64, v21, v20, 16
	v_alignbit_b32 v65, v22, v21, 16
	v_alignbit_b32 v66, v23, v22, 16
	v_alignbit_b32 v67, v20, v23, 16
	v_cndmask_b32_e64 v20, v20, v64, s[18:19]
	v_cndmask_b32_e64 v21, v21, v65, s[18:19]
	v_cndmask_b32_e64 v22, v22, v66, s[18:19]
	v_cndmask_b32_e64 v23, v23, v67, s[18:19]
	v_cndmask_b32_e64 v64, v20, v21, s[24:25]
	v_cndmask_b32_e64 v65, v21, v22, s[24:25]
	v_cndmask_b32_e64 v66, v22, v23, s[24:25]
	v_cndmask_b32_e64 v67, v23, v20, s[24:25]
	v_cndmask_b32_e64 v20, v64, v66, s[92:93]
	v_cndmask_b32_e64 v21, v65, v67, s[92:93]
	v_cndmask_b32_e64 v22, v66, v64, s[92:93]
	v_cndmask_b32_e64 v23, v67, v65, s[92:93]
	ds_write_b16 v4, v20 offset:55296
	ds_write_b16_d16_hi v5, v20 offset:55296
	ds_write_b16 v6, v21 offset:55296
	ds_write_b16_d16_hi v7, v21 offset:55296
	ds_write_b16 v8, v22 offset:55296
	ds_write_b16_d16_hi v9, v22 offset:55296
	ds_write_b16 v10, v23 offset:55296
	ds_write_b16_d16_hi v11, v23 offset:55296
	ds_write_b128 v12, v[24:27] offset:9216
	v_alignbit_b32 v64, v29, v28, 16
	v_alignbit_b32 v65, v30, v29, 16
	v_alignbit_b32 v66, v31, v30, 16
	v_alignbit_b32 v67, v28, v31, 16
	v_cndmask_b32_e64 v28, v28, v64, s[18:19]
	v_cndmask_b32_e64 v29, v29, v65, s[18:19]
	v_cndmask_b32_e64 v30, v30, v66, s[18:19]
	v_cndmask_b32_e64 v31, v31, v67, s[18:19]
	v_cndmask_b32_e64 v64, v28, v29, s[24:25]
	v_cndmask_b32_e64 v65, v29, v30, s[24:25]
	v_cndmask_b32_e64 v66, v30, v31, s[24:25]
	v_cndmask_b32_e64 v67, v31, v28, s[24:25]
	v_cndmask_b32_e64 v28, v64, v66, s[92:93]
	v_cndmask_b32_e64 v29, v65, v67, s[92:93]
	v_cndmask_b32_e64 v30, v66, v64, s[92:93]
	v_cndmask_b32_e64 v31, v67, v65, s[92:93]
	ds_write_b16 v4, v28 offset:55424
	ds_write_b16_d16_hi v5, v28 offset:55424
	ds_write_b16 v6, v29 offset:55424
	ds_write_b16_d16_hi v7, v29 offset:55424
	ds_write_b16 v8, v30 offset:55424
	ds_write_b16_d16_hi v9, v30 offset:55424
	ds_write_b16 v10, v31 offset:55424
	ds_write_b16_d16_hi v11, v31 offset:55424
	ds_write_b128 v12, v[32:35] offset:18432
	v_alignbit_b32 v64, v37, v36, 16
	v_alignbit_b32 v65, v38, v37, 16
	v_alignbit_b32 v66, v39, v38, 16
	v_alignbit_b32 v67, v36, v39, 16
	v_cndmask_b32_e64 v36, v36, v64, s[18:19]
	v_cndmask_b32_e64 v37, v37, v65, s[18:19]
	v_cndmask_b32_e64 v38, v38, v66, s[18:19]
	v_cndmask_b32_e64 v39, v39, v67, s[18:19]
	v_cndmask_b32_e64 v64, v36, v37, s[24:25]
	v_cndmask_b32_e64 v65, v37, v38, s[24:25]
	v_cndmask_b32_e64 v66, v38, v39, s[24:25]
	v_cndmask_b32_e64 v67, v39, v36, s[24:25]
	v_cndmask_b32_e64 v36, v64, v66, s[92:93]
	v_cndmask_b32_e64 v37, v65, v67, s[92:93]
	v_cndmask_b32_e64 v38, v66, v64, s[92:93]
	v_cndmask_b32_e64 v39, v67, v65, s[92:93]
	ds_write_b16 v4, v36 offset:55552
	ds_write_b16_d16_hi v5, v36 offset:55552
	ds_write_b16 v6, v37 offset:55552
	ds_write_b16_d16_hi v7, v37 offset:55552
	ds_write_b16 v8, v38 offset:55552
	ds_write_b16_d16_hi v9, v38 offset:55552
	ds_write_b16 v10, v39 offset:55552
	ds_write_b16_d16_hi v11, v39 offset:55552
	ds_write_b128 v12, v[40:43] offset:27648
	v_alignbit_b32 v64, v45, v44, 16
	v_alignbit_b32 v65, v46, v45, 16
	v_alignbit_b32 v66, v47, v46, 16
	v_alignbit_b32 v67, v44, v47, 16
	v_cndmask_b32_e64 v44, v44, v64, s[18:19]
	v_cndmask_b32_e64 v45, v45, v65, s[18:19]
	v_cndmask_b32_e64 v46, v46, v66, s[18:19]
	v_cndmask_b32_e64 v47, v47, v67, s[18:19]
	v_cndmask_b32_e64 v64, v44, v45, s[24:25]
	v_cndmask_b32_e64 v65, v45, v46, s[24:25]
	v_cndmask_b32_e64 v66, v46, v47, s[24:25]
	v_cndmask_b32_e64 v67, v47, v44, s[24:25]
	v_cndmask_b32_e64 v44, v64, v66, s[92:93]
	v_cndmask_b32_e64 v45, v65, v67, s[92:93]
	v_cndmask_b32_e64 v46, v66, v64, s[92:93]
	v_cndmask_b32_e64 v47, v67, v65, s[92:93]
	ds_write_b16 v4, v44 offset:55680
	ds_write_b16_d16_hi v5, v44 offset:55680
	ds_write_b16 v6, v45 offset:55680
	ds_write_b16_d16_hi v7, v45 offset:55680
	ds_write_b16 v8, v46 offset:55680
	ds_write_b16_d16_hi v9, v46 offset:55680
	ds_write_b16 v10, v47 offset:55680
	ds_write_b16_d16_hi v11, v47 offset:55680
	ds_write_b128 v12, v[48:51] offset:36864
	v_alignbit_b32 v64, v53, v52, 16
	v_alignbit_b32 v65, v54, v53, 16
	v_alignbit_b32 v66, v55, v54, 16
	v_alignbit_b32 v67, v52, v55, 16
	v_cndmask_b32_e64 v52, v52, v64, s[18:19]
	v_cndmask_b32_e64 v53, v53, v65, s[18:19]
	v_cndmask_b32_e64 v54, v54, v66, s[18:19]
	v_cndmask_b32_e64 v55, v55, v67, s[18:19]
	v_cndmask_b32_e64 v64, v52, v53, s[24:25]
	v_cndmask_b32_e64 v65, v53, v54, s[24:25]
	v_cndmask_b32_e64 v66, v54, v55, s[24:25]
	v_cndmask_b32_e64 v67, v55, v52, s[24:25]
	v_cndmask_b32_e64 v52, v64, v66, s[92:93]
	v_cndmask_b32_e64 v53, v65, v67, s[92:93]
	v_cndmask_b32_e64 v54, v66, v64, s[92:93]
	v_cndmask_b32_e64 v55, v67, v65, s[92:93]
	ds_write_b16 v4, v52 offset:55808
	ds_write_b16_d16_hi v5, v52 offset:55808
	ds_write_b16 v6, v53 offset:55808
	ds_write_b16_d16_hi v7, v53 offset:55808
	ds_write_b16 v8, v54 offset:55808
	ds_write_b16_d16_hi v9, v54 offset:55808
	ds_write_b16 v10, v55 offset:55808
	ds_write_b16_d16_hi v11, v55 offset:55808
	ds_write_b128 v12, v[56:59] offset:46080
	v_alignbit_b32 v64, v61, v60, 16
	v_alignbit_b32 v65, v62, v61, 16
	v_alignbit_b32 v66, v63, v62, 16
	v_alignbit_b32 v67, v60, v63, 16
	v_cndmask_b32_e64 v60, v60, v64, s[18:19]
	v_cndmask_b32_e64 v61, v61, v65, s[18:19]
	v_cndmask_b32_e64 v62, v62, v66, s[18:19]
	v_cndmask_b32_e64 v63, v63, v67, s[18:19]
	v_cndmask_b32_e64 v64, v60, v61, s[24:25]
	v_cndmask_b32_e64 v65, v61, v62, s[24:25]
	v_cndmask_b32_e64 v66, v62, v63, s[24:25]
	v_cndmask_b32_e64 v67, v63, v60, s[24:25]
	v_cndmask_b32_e64 v60, v64, v66, s[92:93]
	v_cndmask_b32_e64 v61, v65, v67, s[92:93]
	v_cndmask_b32_e64 v62, v66, v64, s[92:93]
	v_cndmask_b32_e64 v63, v67, v65, s[92:93]
	ds_write_b16 v4, v60 offset:55936
	ds_write_b16_d16_hi v5, v60 offset:55936
	ds_write_b16 v6, v61 offset:55936
	ds_write_b16_d16_hi v7, v61 offset:55936
	ds_write_b16 v8, v62 offset:55936
	ds_write_b16_d16_hi v9, v62 offset:55936
	ds_write_b16 v10, v63 offset:55936
	ds_write_b16_d16_hi v11, v63 offset:55936
